# v81 + MLA loop: LDS wait moved behind the second K-fragment read group as a counted wait lgkmcnt(6) (sec 7.2 wait to first consumer)
# baseline (speedup 1.0000x reference)
; #define SBAR() __builtin_amdgcn_sched_barrier(0)
; #define ATT_DMA_K(t) do { const bf16_t* kg_ = Kh + (size_t)(t) * 64 * LDK; LAS unsigned char* sb_ = lds + ((t) & 3) * KBUF; \
;     _Pragma("unroll") for (int i_ = 0; i_ < NKP; ++i_) __builtin_amdgcn_global_load_lds((const unsigned*)(kg_ + kgo[i_]), (LAS unsigned*)(sb_ + (wid + 8 * i_) * 1024), 16, 0, 0); } while (0)
; #define ATT_DMA_V(t, vs) do { const bf16_t* vg_ = Vh + (size_t)(t) * 64 * LDV; LAS unsigned char* sb_ = lds + V_OFF + (vs) * SHM_V; \
;     _Pragma("unroll") for (int i_ = 0; i_ < 2; ++i_) __builtin_amdgcn_global_load_lds((const unsigned*)(vg_ + vgo[i_]), (LAS unsigned*)(sb_ + (2 * wid + i_) * 1024), 16, 0, 0); } while (0)
; #define ATT_SEG(t) do { if constexpr (MODE != 0) { if (((t) == tL && tL > 0) || (t) == tR) { const float f_ = (t) == tR ? fR : fL; l_reg *= f_; \
;     _Pragma("unroll") for (int d = 0; d < 4; ++d) _Pragma("unroll") for (int r = 0; r < 16; ++r) o[d][r] *= f_; } } } while (0)
; #define ATT_BIAS(P, t, half) do { if constexpr (MODE != 0) { if ((t) >= tL && (t) < tR) { const LAS float* bp_ = bt + ((t) * 64 + (half) * 32 - qpos + 224 + 4 * hi);     \
;     _Pragma("unroll") for (int r = 0; r < 16; ++r) P[r] += bp_[(r & 3) + 8 * (r >> 2)]; } } } while (0)
; #define ATT_TOP(N) do { asm volatile("s_waitcnt vmcnt(%0)" :: "n"(N) : "memory"); __builtin_amdgcn_s_barrier(); asm volatile("" ::: "memory"); } while (0)
; template <int DQK, int MODE, int LDQ, int LDK, int LDV> ...
;     ...
;     f32x16 pA, pB; bf16x8 pa0, pa1;
;     int v0 = 0, v1 = 1, v2 = 2;
;     ATT_TOP(NKP + 2);
;     { bf16x8 kf[NDA]; k_reads<DQK, 0, NDA>(kf, lds, 0, r32, hi); ATT_LGKM0(); qk_mma<0, NDA>(pA, kf, qr);
;       if constexpr (ND0 > NDA) { bf16x8 kg[ND0 - NDA]; k_reads<DQK, NDA, ND0>(kg, lds, 0, r32, hi); ATT_LGKM0(); qk_mma<NDA, ND0>(pA, kg, qr); }
;       ATT_BIAS(pA, 0, 0); }
;     if (wid >= 4) __builtin_amdgcn_s_setprio(1);
;     for (int j = 0; j < NT; ++j) {
;         if (j + 2 < NT) ATT_TOP(NKP + 2); else ATT_TOP(0);
;         if (j + 3 < NT) ATT_DMA_K(j + 3);
;         if (j + 2 < NT) ATT_DMA_V(j + 2, v2);
;         ATT_SEG(j); SBAR();
;         ATT_STEP(pA, pB, 0, v0, true, 1, j);
;         ATT_STEP(pB, pA, 1, v0, (j + 1 < NT), 0, j + 1);
;         { const int t_ = v0; v0 = v1; v1 = v2; v2 = t_; }
;     }
.Lhw_mla_b_n1982:
	s_and_b32 s1, s43, 3
	s_mulk_i32 s1, 0x6000
	s_add_i32 s1, s49, s1
	s_setprio 0
	s_mov_b32 m0, s1
	s_mov_b32 s0, s5
	s_mov_b32 s5, s44
	s_mov_b32 s44, s4
	s_lshl_b32 s4, s4, 14
	global_load_lds_dwordx4 v136, s[34:35]
	s_add_i32 m0, s1, 0x2000
	s_add_i32 s4, s52, s4
	global_load_lds_dwordx4 v138, s[34:35]
	s_add_i32 m0, s1, 0x4000
	s_add_i32 s6, s4, 0x400
	global_load_lds_dwordx4 v140, s[34:35]
	s_mov_b32 m0, s4
	s_add_i32 s1, s43, -3
	global_load_lds_dwordx4 v144, s[34:35]
	s_mov_b32 m0, s6
	s_nop 0
	global_load_lds_dwordx4 v142, s[34:35]
	s_and_b32 s1, s1, 3
	s_mulk_i32 s1, 0x6000
	v_add_u32_e32 v246, s1, v158
	v_add_u32_e32 v250, v246, v151
	v_add_u32_e32 v251, v246, v149
	v_add_u32_e32 v252, v246, v148
	v_add_u32_e32 v253, v246, v147
	s_lshl_b32 s1, s0, 14
	ds_read_b128 v[190:193], v250 offset:12416
	ds_read_b128 v[194:197], v251 offset:12416
	ds_read_b128 v[174:177], v250 offset:12288
	ds_read_b128 v[178:181], v251 offset:12288
	ds_read_b128 v[182:185], v252 offset:12288
	ds_read_b128 v[186:189], v253 offset:12288
	v_add_u32_e32 v254, s1, v130
	ds_read_b64_tr_b16 v[198:199], v254 offset:0
	ds_read_b64_tr_b16 v[200:201], v254 offset:0x800
	ds_read_b64_tr_b16 v[202:203], v254 offset:0x1000
	ds_read_b64_tr_b16 v[204:205], v254 offset:0x1800
	ds_read_b64_tr_b16 v[206:207], v254 offset:0x200
	ds_read_b64_tr_b16 v[208:209], v254 offset:0xa00
	ds_read_b64_tr_b16 v[210:211], v254 offset:0x1200
	ds_read_b64_tr_b16 v[212:213], v254 offset:0x1a00
	ds_read_b64_tr_b16 v[214:215], v254 offset:0x400
	ds_read_b64_tr_b16 v[216:217], v254 offset:0xc00
	ds_read_b64_tr_b16 v[218:219], v254 offset:0x1400
	ds_read_b64_tr_b16 v[220:221], v254 offset:0x1c00
	ds_read_b64_tr_b16 v[222:223], v254 offset:0x600
	ds_read_b64_tr_b16 v[224:225], v254 offset:0xe00
	ds_read_b64_tr_b16 v[226:227], v254 offset:0x1600
	ds_read_b64_tr_b16 v[228:229], v254 offset:0x1e00
	s_setprio 1
	v_exp_f32_e32 v64, v64
	v_exp_f32_e32 v65, v65
	v_exp_f32_e32 v66, v66
	v_exp_f32_e32 v67, v67
	v_exp_f32_e32 v68, v68
	v_exp_f32_e32 v69, v69
	v_add_f32_e32 v230, v65, v64
	v_exp_f32_e32 v70, v70
	v_add_f32_e32 v230, v66, v230
	v_exp_f32_e32 v71, v71
	v_add_f32_e32 v230, v67, v230
	v_exp_f32_e32 v72, v72
	v_add_f32_e32 v230, v68, v230
	v_exp_f32_e32 v73, v73
	v_add_f32_e32 v230, v69, v230
	v_exp_f32_e32 v74, v74
	v_add_f32_e32 v230, v70, v230
	v_exp_f32_e32 v75, v75
	v_add_f32_e32 v230, v71, v230
	v_exp_f32_e32 v76, v76
	v_add_f32_e32 v230, v72, v230
	v_exp_f32_e32 v77, v77
	v_add_f32_e32 v230, v73, v230
	v_exp_f32_e32 v78, v78
	v_add_f32_e32 v230, v74, v230
	v_exp_f32_e32 v79, v79
	v_add_f32_e32 v230, v75, v230
	v_add_f32_e32 v230, v76, v230
	v_add_f32_e32 v230, v77, v230
	v_add_f32_e32 v230, v78, v230
	v_add_f32_e32 v230, v79, v230
	v_add_f32_e32 v173, v173, v230
	v_cvt_pk_bf16_f32 v64, v64, v65
	v_cvt_pk_bf16_f32 v65, v66, v67
	v_cvt_pk_bf16_f32 v66, v68, v69
	v_cvt_pk_bf16_f32 v67, v70, v71
	v_cvt_pk_bf16_f32 v68, v72, v73
	v_cvt_pk_bf16_f32 v69, v74, v75
	v_cvt_pk_bf16_f32 v70, v76, v77
	v_cvt_pk_bf16_f32 v71, v78, v79
	ds_read_b128 v[230:233], v252 offset:12416
	ds_read_b128 v[234:237], v253 offset:12416
	ds_read_b128 v[238:241], v250 offset:12544
	ds_read_b128 v[242:245], v251 offset:12544
	ds_read_b128 v[246:249], v252 offset:12544
	ds_read_b128 v[250:253], v253 offset:12544
	s_waitcnt lgkmcnt(6)
	s_setprio 2
	v_mfma_f32_32x32x16_bf16 v[48:63], v[64:67], v[198:201], v[48:63]
	v_mfma_f32_32x32x16_bf16 v[32:47], v[64:67], v[206:209], v[32:47]
	v_mfma_f32_32x32x16_bf16 v[16:31], v[64:67], v[214:217], v[16:31]
	v_mfma_f32_32x32x16_bf16 v[0:15], v[64:67], v[222:225], v[0:15]
	v_mfma_f32_32x32x16_bf16 v[48:63], v[68:71], v[202:205], v[48:63]
	v_mfma_f32_32x32x16_bf16 v[32:47], v[68:71], v[210:213], v[32:47]
	v_mfma_f32_32x32x16_bf16 v[16:31], v[68:71], v[218:221], v[16:31]
	v_mfma_f32_32x32x16_bf16 v[0:15], v[68:71], v[226:229], v[0:15]
	s_waitcnt lgkmcnt(0)
	v_mfma_f32_32x32x16_bf16 v[64:79], v[174:177], v[80:83], 0
	v_mfma_f32_32x32x16_bf16 v[64:79], v[178:181], v[84:87], v[64:79]
	v_mfma_f32_32x32x16_bf16 v[64:79], v[182:185], v[88:91], v[64:79]
	v_mfma_f32_32x32x16_bf16 v[64:79], v[186:189], v[92:95], v[64:79]
	v_mfma_f32_32x32x16_bf16 v[64:79], v[190:193], v[96:99], v[64:79]
	v_mfma_f32_32x32x16_bf16 v[64:79], v[194:197], v[100:103], v[64:79]
	v_mfma_f32_32x32x16_bf16 v[64:79], v[230:233], v[104:107], v[64:79]
	v_mfma_f32_32x32x16_bf16 v[64:79], v[234:237], v[108:111], v[64:79]
	v_mfma_f32_32x32x16_bf16 v[64:79], v[238:241], v[112:115], v[64:79]
	v_mfma_f32_32x32x16_bf16 v[64:79], v[242:245], v[116:119], v[64:79]
	v_mfma_f32_32x32x16_bf16 v[64:79], v[246:249], v[120:123], v[64:79]
	v_mfma_f32_32x32x16_bf16 v[64:79], v[250:253], v[124:127], v[64:79]
	s_setprio 0
	s_add_i32 s4, s43, -2
	s_and_b32 s4, s4, 3
	s_mulk_i32 s4, 0x6000
	v_add_u32_e32 v246, s4, v158
	v_add_u32_e32 v250, v246, v151
	v_add_u32_e32 v251, v246, v149
	v_add_u32_e32 v252, v246, v148
	v_add_u32_e32 v253, v246, v147
	ds_read_b128 v[190:193], v250 offset:128
	ds_read_b128 v[194:197], v251 offset:128
	ds_read_b128 v[174:177], v250
	ds_read_b128 v[178:181], v251
	ds_read_b128 v[182:185], v252
	ds_read_b128 v[186:189], v253
	ds_read_b64_tr_b16 v[198:199], v254 offset:0x2000
	ds_read_b64_tr_b16 v[200:201], v254 offset:0x2800
	ds_read_b64_tr_b16 v[202:203], v254 offset:0x3000
	ds_read_b64_tr_b16 v[204:205], v254 offset:0x3800
	ds_read_b64_tr_b16 v[206:207], v254 offset:0x2200
	ds_read_b64_tr_b16 v[208:209], v254 offset:0x2a00
	ds_read_b64_tr_b16 v[210:211], v254 offset:0x3200
	ds_read_b64_tr_b16 v[212:213], v254 offset:0x3a00
	ds_read_b64_tr_b16 v[214:215], v254 offset:0x2400
	ds_read_b64_tr_b16 v[216:217], v254 offset:0x2c00
; #define SBAR() __builtin_amdgcn_sched_barrier(0)
; #define ATT_DMA_K(t) do { const bf16_t* kg_ = Kh + (size_t)(t) * 64 * LDK; LAS unsigned char* sb_ = lds + ((t) & 3) * KBUF; \
;     _Pragma("unroll") for (int i_ = 0; i_ < NKP; ++i_) __builtin_amdgcn_global_load_lds((const unsigned*)(kg_ + kgo[i_]), (LAS unsigned*)(sb_ + (wid + 8 * i_) * 1024), 16, 0, 0); } while (0)
; #define ATT_DMA_V(t, vs) do { const bf16_t* vg_ = Vh + (size_t)(t) * 64 * LDV; LAS unsigned char* sb_ = lds + V_OFF + (vs) * SHM_V; \
;     _Pragma("unroll") for (int i_ = 0; i_ < 2; ++i_) __builtin_amdgcn_global_load_lds((const unsigned*)(vg_ + vgo[i_]), (LAS unsigned*)(sb_ + (2 * wid + i_) * 1024), 16, 0, 0); } while (0)
; #define ATT_SEG(t) do { if constexpr (MODE != 0) { if (((t) == tL && tL > 0) || (t) == tR) { const float f_ = (t) == tR ? fR : fL; l_reg *= f_; \
;     _Pragma("unroll") for (int d = 0; d < 4; ++d) _Pragma("unroll") for (int r = 0; r < 16; ++r) o[d][r] *= f_; } } } while (0)
; #define ATT_BIAS(P, t, half) do { if constexpr (MODE != 0) { if ((t) >= tL && (t) < tR) { const LAS float* bp_ = bt + ((t) * 64 + (half) * 32 - qpos + 224 + 4 * hi);     \
;     _Pragma("unroll") for (int r = 0; r < 16; ++r) P[r] += bp_[(r & 3) + 8 * (r >> 2)]; } } } while (0)
; #define ATT_TOP(N) do { asm volatile("s_waitcnt vmcnt(%0)" :: "n"(N) : "memory"); __builtin_amdgcn_s_barrier(); asm volatile("" ::: "memory"); } while (0)
; template <int DQK, int MODE, int LDQ, int LDK, int LDV> ...
;     ...
;     f32x16 pA, pB; bf16x8 pa0, pa1;
;     int v0 = 0, v1 = 1, v2 = 2;
;     ATT_TOP(NKP + 2);
;     { bf16x8 kf[NDA]; k_reads<DQK, 0, NDA>(kf, lds, 0, r32, hi); ATT_LGKM0(); qk_mma<0, NDA>(pA, kf, qr);
;       if constexpr (ND0 > NDA) { bf16x8 kg[ND0 - NDA]; k_reads<DQK, NDA, ND0>(kg, lds, 0, r32, hi); ATT_LGKM0(); qk_mma<NDA, ND0>(pA, kg, qr); }
;       ATT_BIAS(pA, 0, 0); }
;     if (wid >= 4) __builtin_amdgcn_s_setprio(1);
;     for (int j = 0; j < NT; ++j) {
;         if (j + 2 < NT) ATT_TOP(NKP + 2); else ATT_TOP(0);
;         if (j + 3 < NT) ATT_DMA_K(j + 3);
;         if (j + 2 < NT) ATT_DMA_V(j + 2, v2);
;         ATT_SEG(j); SBAR();
;         ATT_STEP(pA, pB, 0, v0, true, 1, j);
;         ATT_STEP(pB, pA, 1, v0, (j + 1 < NT), 0, j + 1);
;         { const int t_ = v0; v0 = v1; v1 = v2; v2 = t_; }
;     }
	ds_read_b64_tr_b16 v[218:219], v254 offset:0x3400
	ds_read_b64_tr_b16 v[220:221], v254 offset:0x3c00
	ds_read_b64_tr_b16 v[222:223], v254 offset:0x2600
	ds_read_b64_tr_b16 v[224:225], v254 offset:0x2e00
	ds_read_b64_tr_b16 v[226:227], v254 offset:0x3600
	ds_read_b64_tr_b16 v[228:229], v254 offset:0x3e00
	s_setprio 1
	v_exp_f32_e32 v64, v64
	v_exp_f32_e32 v65, v65
	v_exp_f32_e32 v66, v66
	v_exp_f32_e32 v67, v67
	v_exp_f32_e32 v68, v68
	v_exp_f32_e32 v69, v69
	v_add_f32_e32 v230, v65, v64
	v_exp_f32_e32 v70, v70
	v_add_f32_e32 v230, v66, v230
	v_exp_f32_e32 v71, v71
	v_add_f32_e32 v230, v67, v230
	v_exp_f32_e32 v72, v72
	v_add_f32_e32 v230, v68, v230
	v_exp_f32_e32 v73, v73
	v_add_f32_e32 v230, v69, v230
	v_exp_f32_e32 v74, v74
	v_add_f32_e32 v230, v70, v230
	v_exp_f32_e32 v75, v75
	v_add_f32_e32 v230, v71, v230
	v_exp_f32_e32 v76, v76
	v_add_f32_e32 v230, v72, v230
	v_exp_f32_e32 v77, v77
	v_add_f32_e32 v230, v73, v230
	v_exp_f32_e32 v78, v78
	v_add_f32_e32 v230, v74, v230
	v_exp_f32_e32 v79, v79
	v_add_f32_e32 v230, v75, v230
	v_add_f32_e32 v230, v76, v230
	v_add_f32_e32 v230, v77, v230
	v_add_f32_e32 v230, v78, v230
	v_add_f32_e32 v230, v79, v230
	v_add_f32_e32 v173, v173, v230
	v_cvt_pk_bf16_f32 v64, v64, v65
	v_cvt_pk_bf16_f32 v65, v66, v67
	v_cvt_pk_bf16_f32 v66, v68, v69
	v_cvt_pk_bf16_f32 v67, v70, v71
	v_cvt_pk_bf16_f32 v68, v72, v73
	v_cvt_pk_bf16_f32 v69, v74, v75
	v_cvt_pk_bf16_f32 v70, v76, v77
	v_cvt_pk_bf16_f32 v71, v78, v79
	ds_read_b128 v[230:233], v252 offset:128
	ds_read_b128 v[234:237], v253 offset:128
	ds_read_b128 v[238:241], v250 offset:256
	ds_read_b128 v[242:245], v251 offset:256
	ds_read_b128 v[246:249], v252 offset:256
	ds_read_b128 v[250:253], v253 offset:256
	s_waitcnt lgkmcnt(6)
	s_setprio 2
	s_waitcnt vmcnt(5)
	s_barrier
	v_mfma_f32_32x32x16_bf16 v[48:63], v[64:67], v[198:201], v[48:63]
	v_mfma_f32_32x32x16_bf16 v[32:47], v[64:67], v[206:209], v[32:47]
	v_mfma_f32_32x32x16_bf16 v[16:31], v[64:67], v[214:217], v[16:31]
	v_mfma_f32_32x32x16_bf16 v[0:15], v[64:67], v[222:225], v[0:15]
	v_mfma_f32_32x32x16_bf16 v[48:63], v[68:71], v[202:205], v[48:63]
	v_mfma_f32_32x32x16_bf16 v[32:47], v[68:71], v[210:213], v[32:47]
	v_mfma_f32_32x32x16_bf16 v[16:31], v[68:71], v[218:221], v[16:31]
	v_mfma_f32_32x32x16_bf16 v[0:15], v[68:71], v[226:229], v[0:15]
	s_waitcnt lgkmcnt(0)
	v_mfma_f32_32x32x16_bf16 v[64:79], v[174:177], v[80:83], 0
	v_mfma_f32_32x32x16_bf16 v[64:79], v[178:181], v[84:87], v[64:79]
	v_mfma_f32_32x32x16_bf16 v[64:79], v[182:185], v[88:91], v[64:79]
	v_mfma_f32_32x32x16_bf16 v[64:79], v[186:189], v[92:95], v[64:79]
	v_mfma_f32_32x32x16_bf16 v[64:79], v[190:193], v[96:99], v[64:79]
	v_mfma_f32_32x32x16_bf16 v[64:79], v[194:197], v[100:103], v[64:79]
	v_mfma_f32_32x32x16_bf16 v[64:79], v[230:233], v[104:107], v[64:79]
	v_mfma_f32_32x32x16_bf16 v[64:79], v[234:237], v[108:111], v[64:79]
	v_mfma_f32_32x32x16_bf16 v[64:79], v[238:241], v[112:115], v[64:79]
	v_mfma_f32_32x32x16_bf16 v[64:79], v[242:245], v[116:119], v[64:79]
	v_mfma_f32_32x32x16_bf16 v[64:79], v[246:249], v[120:123], v[64:79]
	v_mfma_f32_32x32x16_bf16 v[64:79], v[250:253], v[124:127], v[64:79]
	s_add_i32 s43, s43, 1
	v_add_u32_e32 v136, s36, v136
	v_add_u32_e32 v138, s36, v138
	v_add_u32_e32 v140, s36, v140
	v_add_u32_e32 v142, s38, v142
	v_add_u32_e32 v144, s38, v144
	s_cmp_eq_u32 s43, 64
	s_mov_b32 s4, s0
	s_cbranch_scc0 .Lhw_mla_b_n1982
	s_branch .Lhw_mla_exit
.LBB0_1982:
	s_and_b32 s1, s43, 3
	s_mulk_i32 s1, 0x6000
	s_add_i32 s1, s49, s1
	s_waitcnt vmcnt(5)
	s_barrier
	s_setprio 0
	s_mov_b32 m0, s1
	s_mov_b32 s0, s5
	s_mov_b32 s5, s44
	s_mov_b32 s44, s4
	s_lshl_b32 s4, s4, 14
	global_load_lds_dwordx4 v136, s[34:35]
	s_add_i32 m0, s1, 0x2000
	s_add_i32 s4, s52, s4
	global_load_lds_dwordx4 v138, s[34:35]
	s_add_i32 m0, s1, 0x4000
	s_add_i32 s6, s4, 0x400
	global_load_lds_dwordx4 v140, s[34:35]
	s_mov_b32 m0, s4
	s_add_i32 s1, s43, -3
	global_load_lds_dwordx4 v144, s[34:35]
	s_mov_b32 m0, s6
	s_nop 0
	global_load_lds_dwordx4 v142, s[34:35]
	s_and_b32 s1, s1, 3
	s_mulk_i32 s1, 0x6000
	v_add_u32_e32 v246, s1, v158
	v_add_u32_e32 v250, v246, v151
	v_add_u32_e32 v251, v246, v149
	v_add_u32_e32 v252, v246, v148
	v_add_u32_e32 v253, v246, v147
	s_lshl_b32 s1, s0, 14
	ds_read_b128 v[190:193], v250 offset:12416
	ds_read_b128 v[194:197], v251 offset:12416
	ds_read_b128 v[174:177], v250 offset:12288
	ds_read_b128 v[178:181], v251 offset:12288
	ds_read_b128 v[182:185], v252 offset:12288
	ds_read_b128 v[186:189], v253 offset:12288
	v_add_u32_e32 v254, s1, v130
	ds_read_b64_tr_b16 v[198:199], v254 offset:0
	ds_read_b64_tr_b16 v[200:201], v254 offset:0x800
	ds_read_b64_tr_b16 v[202:203], v254 offset:0x1000
	ds_read_b64_tr_b16 v[204:205], v254 offset:0x1800
	ds_read_b64_tr_b16 v[206:207], v254 offset:0x200
	ds_read_b64_tr_b16 v[208:209], v254 offset:0xa00
	ds_read_b64_tr_b16 v[210:211], v254 offset:0x1200
	ds_read_b64_tr_b16 v[212:213], v254 offset:0x1a00
	ds_read_b64_tr_b16 v[214:215], v254 offset:0x400
	ds_read_b64_tr_b16 v[216:217], v254 offset:0xc00
	ds_read_b64_tr_b16 v[218:219], v254 offset:0x1400
	ds_read_b64_tr_b16 v[220:221], v254 offset:0x1c00
	ds_read_b64_tr_b16 v[222:223], v254 offset:0x600
	ds_read_b64_tr_b16 v[224:225], v254 offset:0xe00
	ds_read_b64_tr_b16 v[226:227], v254 offset:0x1600
	ds_read_b64_tr_b16 v[228:229], v254 offset:0x1e00
	s_setprio 1
	v_exp_f32_e32 v64, v64
	v_exp_f32_e32 v65, v65
	v_exp_f32_e32 v66, v66
	v_exp_f32_e32 v67, v67
	v_exp_f32_e32 v68, v68
	v_exp_f32_e32 v69, v69
	v_add_f32_e32 v230, v65, v64
	v_exp_f32_e32 v70, v70
	v_add_f32_e32 v230, v66, v230
	v_exp_f32_e32 v71, v71
	v_add_f32_e32 v230, v67, v230
	v_exp_f32_e32 v72, v72
	v_add_f32_e32 v230, v68, v230
	v_exp_f32_e32 v73, v73
	v_add_f32_e32 v230, v69, v230
	v_exp_f32_e32 v74, v74
	v_add_f32_e32 v230, v70, v230
	v_exp_f32_e32 v75, v75
	v_add_f32_e32 v230, v71, v230
	v_exp_f32_e32 v76, v76
	v_add_f32_e32 v230, v72, v230
	v_exp_f32_e32 v77, v77
	v_add_f32_e32 v230, v73, v230
	v_exp_f32_e32 v78, v78
	v_add_f32_e32 v230, v74, v230
	v_exp_f32_e32 v79, v79
	v_add_f32_e32 v230, v75, v230
	v_add_f32_e32 v230, v76, v230
	v_add_f32_e32 v230, v77, v230
	v_add_f32_e32 v230, v78, v230
	v_add_f32_e32 v230, v79, v230
	v_add_f32_e32 v173, v173, v230
	v_cvt_pk_bf16_f32 v64, v64, v65
	v_cvt_pk_bf16_f32 v65, v66, v67
	v_cvt_pk_bf16_f32 v66, v68, v69
	v_cvt_pk_bf16_f32 v67, v70, v71
	v_cvt_pk_bf16_f32 v68, v72, v73
	v_cvt_pk_bf16_f32 v69, v74, v75
	v_cvt_pk_bf16_f32 v70, v76, v77
	v_cvt_pk_bf16_f32 v71, v78, v79
	ds_read_b128 v[230:233], v252 offset:12416
	ds_read_b128 v[234:237], v253 offset:12416
	ds_read_b128 v[238:241], v250 offset:12544
	ds_read_b128 v[242:245], v251 offset:12544
	ds_read_b128 v[246:249], v252 offset:12544
	ds_read_b128 v[250:253], v253 offset:12544
	s_waitcnt lgkmcnt(6)
; #define SBAR() __builtin_amdgcn_sched_barrier(0)
; #define ATT_DMA_K(t) do { const bf16_t* kg_ = Kh + (size_t)(t) * 64 * LDK; LAS unsigned char* sb_ = lds + ((t) & 3) * KBUF; \
;     _Pragma("unroll") for (int i_ = 0; i_ < NKP; ++i_) __builtin_amdgcn_global_load_lds((const unsigned*)(kg_ + kgo[i_]), (LAS unsigned*)(sb_ + (wid + 8 * i_) * 1024), 16, 0, 0); } while (0)
; #define ATT_DMA_V(t, vs) do { const bf16_t* vg_ = Vh + (size_t)(t) * 64 * LDV; LAS unsigned char* sb_ = lds + V_OFF + (vs) * SHM_V; \
;     _Pragma("unroll") for (int i_ = 0; i_ < 2; ++i_) __builtin_amdgcn_global_load_lds((const unsigned*)(vg_ + vgo[i_]), (LAS unsigned*)(sb_ + (2 * wid + i_) * 1024), 16, 0, 0); } while (0)
; #define ATT_SEG(t) do { if constexpr (MODE != 0) { if (((t) == tL && tL > 0) || (t) == tR) { const float f_ = (t) == tR ? fR : fL; l_reg *= f_; \
;     _Pragma("unroll") for (int d = 0; d < 4; ++d) _Pragma("unroll") for (int r = 0; r < 16; ++r) o[d][r] *= f_; } } } while (0)
; #define ATT_BIAS(P, t, half) do { if constexpr (MODE != 0) { if ((t) >= tL && (t) < tR) { const LAS float* bp_ = bt + ((t) * 64 + (half) * 32 - qpos + 224 + 4 * hi);     \
;     _Pragma("unroll") for (int r = 0; r < 16; ++r) P[r] += bp_[(r & 3) + 8 * (r >> 2)]; } } } while (0)
; #define ATT_TOP(N) do { asm volatile("s_waitcnt vmcnt(%0)" :: "n"(N) : "memory"); __builtin_amdgcn_s_barrier(); asm volatile("" ::: "memory"); } while (0)
; template <int DQK, int MODE, int LDQ, int LDK, int LDV> ...
;     ...
;     f32x16 pA, pB; bf16x8 pa0, pa1;
;     int v0 = 0, v1 = 1, v2 = 2;
;     ATT_TOP(NKP + 2);
;     { bf16x8 kf[NDA]; k_reads<DQK, 0, NDA>(kf, lds, 0, r32, hi); ATT_LGKM0(); qk_mma<0, NDA>(pA, kf, qr);
;       if constexpr (ND0 > NDA) { bf16x8 kg[ND0 - NDA]; k_reads<DQK, NDA, ND0>(kg, lds, 0, r32, hi); ATT_LGKM0(); qk_mma<NDA, ND0>(pA, kg, qr); }
;       ATT_BIAS(pA, 0, 0); }
;     if (wid >= 4) __builtin_amdgcn_s_setprio(1);
;     for (int j = 0; j < NT; ++j) {
;         if (j + 2 < NT) ATT_TOP(NKP + 2); else ATT_TOP(0);
;         if (j + 3 < NT) ATT_DMA_K(j + 3);
;         if (j + 2 < NT) ATT_DMA_V(j + 2, v2);
;         ATT_SEG(j); SBAR();
;         ATT_STEP(pA, pB, 0, v0, true, 1, j);
;         ATT_STEP(pB, pA, 1, v0, (j + 1 < NT), 0, j + 1);
;         { const int t_ = v0; v0 = v1; v1 = v2; v2 = t_; }
;     }
	s_setprio 2
	v_mfma_f32_32x32x16_bf16 v[48:63], v[64:67], v[198:201], v[48:63]
	v_mfma_f32_32x32x16_bf16 v[32:47], v[64:67], v[206:209], v[32:47]
	v_mfma_f32_32x32x16_bf16 v[16:31], v[64:67], v[214:217], v[16:31]
	v_mfma_f32_32x32x16_bf16 v[0:15], v[64:67], v[222:225], v[0:15]
	v_mfma_f32_32x32x16_bf16 v[48:63], v[68:71], v[202:205], v[48:63]
	v_mfma_f32_32x32x16_bf16 v[32:47], v[68:71], v[210:213], v[32:47]
	v_mfma_f32_32x32x16_bf16 v[16:31], v[68:71], v[218:221], v[16:31]
	v_mfma_f32_32x32x16_bf16 v[0:15], v[68:71], v[226:229], v[0:15]
	s_waitcnt lgkmcnt(0)
	v_mfma_f32_32x32x16_bf16 v[64:79], v[174:177], v[80:83], 0
	v_mfma_f32_32x32x16_bf16 v[64:79], v[178:181], v[84:87], v[64:79]
	v_mfma_f32_32x32x16_bf16 v[64:79], v[182:185], v[88:91], v[64:79]
	v_mfma_f32_32x32x16_bf16 v[64:79], v[186:189], v[92:95], v[64:79]
	v_mfma_f32_32x32x16_bf16 v[64:79], v[190:193], v[96:99], v[64:79]
	v_mfma_f32_32x32x16_bf16 v[64:79], v[194:197], v[100:103], v[64:79]
	v_mfma_f32_32x32x16_bf16 v[64:79], v[230:233], v[104:107], v[64:79]
	v_mfma_f32_32x32x16_bf16 v[64:79], v[234:237], v[108:111], v[64:79]
	v_mfma_f32_32x32x16_bf16 v[64:79], v[238:241], v[112:115], v[64:79]
	v_mfma_f32_32x32x16_bf16 v[64:79], v[242:245], v[116:119], v[64:79]
	v_mfma_f32_32x32x16_bf16 v[64:79], v[246:249], v[120:123], v[64:79]
	v_mfma_f32_32x32x16_bf16 v[64:79], v[250:253], v[124:127], v[64:79]
	s_setprio 0
	s_add_i32 s4, s43, -2
	s_and_b32 s4, s4, 3
	s_mulk_i32 s4, 0x6000
	v_add_u32_e32 v246, s4, v158
	v_add_u32_e32 v250, v246, v151
	v_add_u32_e32 v251, v246, v149
	v_add_u32_e32 v252, v246, v148
	v_add_u32_e32 v253, v246, v147
	ds_read_b128 v[190:193], v250 offset:128
	ds_read_b128 v[194:197], v251 offset:128
	ds_read_b128 v[174:177], v250
	ds_read_b128 v[178:181], v251
	ds_read_b128 v[182:185], v252
	ds_read_b128 v[186:189], v253
	ds_read_b64_tr_b16 v[198:199], v254 offset:0x2000
	ds_read_b64_tr_b16 v[200:201], v254 offset:0x2800
	ds_read_b64_tr_b16 v[202:203], v254 offset:0x3000
	ds_read_b64_tr_b16 v[204:205], v254 offset:0x3800
	ds_read_b64_tr_b16 v[206:207], v254 offset:0x2200
	ds_read_b64_tr_b16 v[208:209], v254 offset:0x2a00
	ds_read_b64_tr_b16 v[210:211], v254 offset:0x3200
	ds_read_b64_tr_b16 v[212:213], v254 offset:0x3a00
	ds_read_b64_tr_b16 v[214:215], v254 offset:0x2400
	ds_read_b64_tr_b16 v[216:217], v254 offset:0x2c00
	ds_read_b64_tr_b16 v[218:219], v254 offset:0x3400
	ds_read_b64_tr_b16 v[220:221], v254 offset:0x3c00
	ds_read_b64_tr_b16 v[222:223], v254 offset:0x2600
	ds_read_b64_tr_b16 v[224:225], v254 offset:0x2e00
	ds_read_b64_tr_b16 v[226:227], v254 offset:0x3600
	ds_read_b64_tr_b16 v[228:229], v254 offset:0x3e00
	s_setprio 1
	v_exp_f32_e32 v64, v64
	v_exp_f32_e32 v65, v65
	v_exp_f32_e32 v66, v66
	v_exp_f32_e32 v67, v67
	v_exp_f32_e32 v68, v68
	v_exp_f32_e32 v69, v69
	v_add_f32_e32 v230, v65, v64
	v_exp_f32_e32 v70, v70
	v_add_f32_e32 v230, v66, v230
	v_exp_f32_e32 v71, v71
	v_add_f32_e32 v230, v67, v230
	v_exp_f32_e32 v72, v72
	v_add_f32_e32 v230, v68, v230
	v_exp_f32_e32 v73, v73
	v_add_f32_e32 v230, v69, v230
	v_exp_f32_e32 v74, v74
	v_add_f32_e32 v230, v70, v230
	v_exp_f32_e32 v75, v75
	v_add_f32_e32 v230, v71, v230
	v_exp_f32_e32 v76, v76
	v_add_f32_e32 v230, v72, v230
	v_exp_f32_e32 v77, v77
	v_add_f32_e32 v230, v73, v230
	v_exp_f32_e32 v78, v78
	v_add_f32_e32 v230, v74, v230
	v_exp_f32_e32 v79, v79
	v_add_f32_e32 v230, v75, v230
	v_add_f32_e32 v230, v76, v230
	v_add_f32_e32 v230, v77, v230
	v_add_f32_e32 v230, v78, v230
	v_add_f32_e32 v230, v79, v230
	v_add_f32_e32 v173, v173, v230
	v_cvt_pk_bf16_f32 v64, v64, v65
	v_cvt_pk_bf16_f32 v65, v66, v67
	v_cvt_pk_bf16_f32 v66, v68, v69
	v_cvt_pk_bf16_f32 v67, v70, v71
	v_cvt_pk_bf16_f32 v68, v72, v73
	v_cvt_pk_bf16_f32 v69, v74, v75
	v_cvt_pk_bf16_f32 v70, v76, v77
	v_cvt_pk_bf16_f32 v71, v78, v79
	ds_read_b128 v[230:233], v252 offset:128
	ds_read_b128 v[234:237], v253 offset:128
	ds_read_b128 v[238:241], v250 offset:256
	ds_read_b128 v[242:245], v251 offset:256
	ds_read_b128 v[246:249], v252 offset:256
	ds_read_b128 v[250:253], v253 offset:256
	s_waitcnt lgkmcnt(6)
	s_setprio 2
	v_mfma_f32_32x32x16_bf16 v[48:63], v[64:67], v[198:201], v[48:63]
	v_mfma_f32_32x32x16_bf16 v[32:47], v[64:67], v[206:209], v[32:47]
	v_mfma_f32_32x32x16_bf16 v[16:31], v[64:67], v[214:217], v[16:31]
	v_mfma_f32_32x32x16_bf16 v[0:15], v[64:67], v[222:225], v[0:15]
	v_mfma_f32_32x32x16_bf16 v[48:63], v[68:71], v[202:205], v[48:63]
	v_mfma_f32_32x32x16_bf16 v[32:47], v[68:71], v[210:213], v[32:47]
	v_mfma_f32_32x32x16_bf16 v[16:31], v[68:71], v[218:221], v[16:31]
	v_mfma_f32_32x32x16_bf16 v[0:15], v[68:71], v[226:229], v[0:15]
	s_waitcnt lgkmcnt(0)
	v_mfma_f32_32x32x16_bf16 v[64:79], v[174:177], v[80:83], 0
	v_mfma_f32_32x32x16_bf16 v[64:79], v[178:181], v[84:87], v[64:79]
	v_mfma_f32_32x32x16_bf16 v[64:79], v[182:185], v[88:91], v[64:79]
	v_mfma_f32_32x32x16_bf16 v[64:79], v[186:189], v[92:95], v[64:79]
	v_mfma_f32_32x32x16_bf16 v[64:79], v[190:193], v[96:99], v[64:79]
	v_mfma_f32_32x32x16_bf16 v[64:79], v[194:197], v[100:103], v[64:79]
	v_mfma_f32_32x32x16_bf16 v[64:79], v[230:233], v[104:107], v[64:79]
	v_mfma_f32_32x32x16_bf16 v[64:79], v[234:237], v[108:111], v[64:79]
	v_mfma_f32_32x32x16_bf16 v[64:79], v[238:241], v[112:115], v[64:79]
	v_mfma_f32_32x32x16_bf16 v[64:79], v[242:245], v[116:119], v[64:79]
	v_mfma_f32_32x32x16_bf16 v[64:79], v[246:249], v[120:123], v[64:79]
	v_mfma_f32_32x32x16_bf16 v[64:79], v[250:253], v[124:127], v[64:79]
	s_add_i32 s43, s43, 1
	v_add_u32_e32 v136, s36, v136
	v_add_u32_e32 v138, s36, v138
	v_add_u32_e32 v140, s36, v140
	v_add_u32_e32 v142, s38, v142
	v_add_u32_e32 v144, s38, v144
	s_cmp_eq_u32 s43, 64
	s_mov_b32 s4, s0
	s_cbranch_scc0 .LBB0_1982
